# v24 + gmlp_sample_unit: layer-norm gain/bias loaded once instead of four times (three load round trips and store drains removed)
# baseline (speedup 1.0000x reference)
.LBB0_654:
	s_or_b64 exec, exec, s[30:31]
	s_waitcnt lgkmcnt(0)
	s_barrier
	ds_read_b128 v[2:5], v1
	ds_read_b128 v[34:37], v1 offset:16
	ds_read_b128 v[6:9], v1 offset:32
	ds_read_b128 v[38:41], v1 offset:48
	ds_read_b128 v[10:13], v1 offset:64
	ds_read_b128 v[42:45], v1 offset:80
	ds_read_b128 v[14:17], v1 offset:96
	ds_read_b128 v[46:49], v1 offset:112
	ds_read_b128 v[18:21], v1 offset:128
	ds_read_b128 v[50:53], v1 offset:144
	ds_read_b128 v[22:25], v1 offset:160
	ds_read_b128 v[54:57], v1 offset:176
	ds_read_b128 v[26:29], v1 offset:192
	ds_read_b128 v[58:61], v1 offset:208
	ds_read_b128 v[30:33], v1 offset:224
	ds_read_b128 v[62:65], v1 offset:240
	s_waitcnt lgkmcnt(14)
	v_mov_b32_e32 v72, v34
	v_mov_b32_e32 v73, v2
	v_pk_add_f32 v[72:73], v[72:73], 0 op_sel_hi:[1,0]
	s_waitcnt lgkmcnt(12)
	v_mov_b32_e32 v74, v38
	v_mov_b32_e32 v75, v6
	v_pk_add_f32 v[72:73], v[72:73], v[74:75]
	s_waitcnt lgkmcnt(10)
	v_mov_b32_e32 v74, v42
	v_mov_b32_e32 v75, v10
	v_pk_add_f32 v[72:73], v[72:73], v[74:75]
	s_waitcnt lgkmcnt(8)
	v_mov_b32_e32 v74, v46
	v_mov_b32_e32 v75, v14
	v_pk_add_f32 v[72:73], v[72:73], v[74:75]
	s_waitcnt lgkmcnt(6)
	v_mov_b32_e32 v74, v50
	v_mov_b32_e32 v75, v18
	v_pk_add_f32 v[72:73], v[72:73], v[74:75]
	s_waitcnt lgkmcnt(4)
	v_mov_b32_e32 v74, v54
	v_mov_b32_e32 v75, v22
	v_pk_add_f32 v[72:73], v[72:73], v[74:75]
	s_waitcnt lgkmcnt(2)
	v_mov_b32_e32 v74, v58
	v_mov_b32_e32 v75, v26
	v_pk_add_f32 v[72:73], v[72:73], v[74:75]
	s_waitcnt lgkmcnt(0)
	v_mov_b32_e32 v74, v62
	v_mov_b32_e32 v75, v30
	v_pk_add_f32 v[72:73], v[72:73], v[74:75]
	s_mov_b32 s34, 0x3a800000
	v_pk_mul_f32 v[82:83], v[72:73], s[34:35] op_sel_hi:[1,0]
	v_readlane_b32 s1, v253, 29
	v_fma_f32 v0, -v83, v83, v82
	v_max_f32_e32 v0, 0, v0
	v_add_f32_e32 v0, 0x358637bd, v0
	v_cmp_gt_f32_e32 vcc, s91, v0
	v_mul_f32_e32 v2, 0x4b800000, v0
	v_lshlrev_b64 v[80:81], 2, v[66:67]
	v_cndmask_b32_e32 v0, v0, v2, vcc
	v_rsq_f32_e32 v0, v0
	v_pk_add_f32 v[68:69], v[68:69], v[82:83] op_sel:[0,1] neg_lo:[0,1] neg_hi:[0,1]
	v_mov_b32_e32 v6, v39
	v_mov_b32_e32 v10, v43
	v_mul_f32_e32 v2, 0x45800000, v0
	v_cndmask_b32_e32 v0, v0, v2, vcc
	v_mov_b32_e32 v2, s1
	ds_read_b128 v[72:75], v2
	v_mov_b32_e32 v2, v35
	v_pk_add_f32 v[2:3], v[2:3], 0 op_sel_hi:[1,0]
	v_mov_b32_e32 v14, v47
	v_pk_add_f32 v[2:3], v[2:3], v[6:7]
	s_waitcnt lgkmcnt(0)
	v_lshl_add_u64 v[72:73], v[72:73], 0, v[80:81]
	v_lshl_add_u64 v[74:75], v[74:75], 0, v[80:81]
	global_load_dwordx2 v[82:83], v[72:73], off
	global_load_dwordx2 v[84:85], v[74:75], off
	v_pk_add_f32 v[2:3], v[2:3], v[10:11]
	v_mov_b32_e32 v18, v51
	v_pk_add_f32 v[2:3], v[2:3], v[14:15]
	v_mov_b32_e32 v22, v55
	v_pk_add_f32 v[2:3], v[2:3], v[18:19]
	v_mov_b32_e32 v26, v59
	v_pk_add_f32 v[2:3], v[2:3], v[22:23]
	v_mov_b32_e32 v30, v63
	v_pk_add_f32 v[2:3], v[2:3], v[26:27]
	v_pk_mul_f32 v[68:69], v[68:69], v[0:1] op_sel_hi:[1,0]
	v_pk_add_f32 v[2:3], v[2:3], v[30:31]
	s_lshl_b32 s0, s29, 12
	v_pk_mul_f32 v[2:3], v[2:3], s[34:35] op_sel_hi:[1,0]
	s_mov_b32 s1, s93
	v_fma_f32 v0, -v3, v3, v2
	v_max_f32_e32 v0, 0, v0
	v_add_f32_e32 v0, 0x358637bd, v0
	v_cmp_gt_f32_e32 vcc, s91, v0
	v_mul_f32_e32 v6, 0x4b800000, v0
	s_lshl_b64 s[0:1], s[0:1], 2
	v_cndmask_b32_e32 v0, v0, v6, vcc
	v_rsq_f32_e32 v0, v0
	s_add_u32 s30, s43, s0
	s_addc_u32 s31, s44, s1
	v_pk_add_f32 v[2:3], v[78:79], v[2:3] op_sel:[0,1] neg_lo:[0,1] neg_hi:[0,1]
	v_mul_f32_e32 v6, 0x45800000, v0
	v_cndmask_b32_e32 v0, v0, v6, vcc
	v_pk_mul_f32 v[2:3], v[2:3], v[0:1] op_sel_hi:[1,0]
	v_mov_b32_e32 v18, v40
	v_mov_b32_e32 v19, v8
	v_mov_b32_e32 v8, v41
	s_waitcnt vmcnt(0)
	v_mov_b64_e32 v[100:101], v[82:83]
	v_mov_b64_e32 v[102:103], v[84:85]
	v_pk_fma_f32 v[68:69], v[82:83], v[68:69], v[84:85]
	v_lshl_add_u64 v[82:83], s[30:31], 0, v[80:81]
	global_store_dwordx2 v[82:83], v[68:69], off
	v_mov_b64_e32 v[6:7], v[100:101]
	v_mov_b64_e32 v[10:11], v[102:103]
	v_readlane_b32 s30, v254, 8
	v_readlane_b32 s31, v254, 9
	s_add_u32 s0, s30, s0
	s_addc_u32 s1, s31, s1
	v_pk_fma_f32 v[2:3], v[6:7], v[2:3], v[10:11]
	v_mov_b32_e32 v10, v36
	v_mov_b32_e32 v11, v4
	v_pk_add_f32 v[10:11], v[10:11], 0 op_sel_hi:[1,0]
	v_lshl_add_u64 v[6:7], s[0:1], 0, v[80:81]
	v_pk_add_f32 v[10:11], v[10:11], v[18:19]
	v_mov_b32_e32 v18, v44
	v_mov_b32_e32 v19, v12
	v_pk_add_f32 v[10:11], v[10:11], v[18:19]
	v_mov_b32_e32 v18, v48
	v_mov_b32_e32 v19, v16
	s_mov_b32 s0, 0x8202000
	v_pk_add_f32 v[10:11], v[10:11], v[18:19]
	v_mov_b32_e32 v18, v52
	v_mov_b32_e32 v19, v20
	v_add_co_u32_e32 v14, vcc, s0, v6
	v_pk_add_f32 v[10:11], v[10:11], v[18:19]
	v_mov_b32_e32 v18, v56
	v_mov_b32_e32 v19, v24
	v_addc_co_u32_e32 v15, vcc, 0, v7, vcc
	v_pk_add_f32 v[10:11], v[10:11], v[18:19]
	v_mov_b32_e32 v18, v60
	v_mov_b32_e32 v19, v28
	global_store_dwordx2 v[14:15], v[2:3], off offset:-4096
	v_pk_add_f32 v[10:11], v[10:11], v[18:19]
	v_mov_b32_e32 v18, v64
	v_mov_b32_e32 v19, v32
	v_pk_add_f32 v[10:11], v[10:11], v[18:19]
	v_mov_b64_e32 v[18:19], v[100:101]
	v_mov_b64_e32 v[22:23], v[102:103]
	v_pk_mul_f32 v[10:11], v[10:11], s[34:35] op_sel_hi:[1,0]
	v_mov_b32_e32 v12, v45
	v_fma_f32 v0, -v11, v11, v10
	v_max_f32_e32 v0, 0, v0
	v_add_f32_e32 v0, 0x358637bd, v0
	v_cmp_gt_f32_e32 vcc, s91, v0
	v_mul_f32_e32 v4, 0x4b800000, v0
	v_mov_b32_e32 v16, v49
	v_cndmask_b32_e32 v0, v0, v4, vcc
	v_rsq_f32_e32 v0, v0
	v_mov_b32_e32 v20, v53
	v_mov_b32_e32 v24, v57
	v_mov_b32_e32 v28, v61
	v_mul_f32_e32 v4, 0x45800000, v0
	v_cndmask_b32_e32 v0, v0, v4, vcc
	v_mov_b32_e32 v4, v37
	v_pk_add_f32 v[4:5], v[4:5], 0 op_sel_hi:[1,0]
	v_mov_b32_e32 v32, v65
	v_pk_add_f32 v[4:5], v[4:5], v[8:9]
	v_pk_add_f32 v[10:11], v[76:77], v[10:11] op_sel:[0,1] neg_lo:[0,1] neg_hi:[0,1]
	v_pk_add_f32 v[4:5], v[4:5], v[12:13]
	v_pk_mul_f32 v[10:11], v[10:11], v[0:1] op_sel_hi:[1,0]
	v_pk_add_f32 v[4:5], v[4:5], v[16:17]
	v_pk_fma_f32 v[10:11], v[18:19], v[10:11], v[22:23]
	v_pk_add_f32 v[4:5], v[4:5], v[20:21]
	global_store_dwordx2 v[14:15], v[10:11], off
	v_pk_add_f32 v[4:5], v[4:5], v[24:25]
	s_nop 0
	v_pk_add_f32 v[4:5], v[4:5], v[28:29]
	s_nop 0
	v_pk_add_f32 v[4:5], v[4:5], v[32:33]
	s_nop 0
	v_pk_mul_f32 v[4:5], v[4:5], s[34:35] op_sel_hi:[1,0]
	s_nop 0
	v_fma_f32 v0, -v5, v5, v4
	v_max_f32_e32 v0, 0, v0
	v_add_f32_e32 v0, 0x358637bd, v0
	v_cmp_gt_f32_e32 vcc, s91, v0
	v_mul_f32_e32 v8, 0x4b800000, v0
	v_pk_add_f32 v[4:5], v[70:71], v[4:5] op_sel:[0,1] neg_lo:[0,1] neg_hi:[0,1]
	v_cndmask_b32_e32 v0, v0, v8, vcc
	v_rsq_f32_e32 v0, v0
	s_nop 0
	v_mul_f32_e32 v8, 0x45800000, v0
	v_cndmask_b32_e32 v0, v0, v8, vcc
	v_mov_b64_e32 v[8:9], v[100:101]
	v_mov_b64_e32 v[12:13], v[102:103]
	v_add_co_u32_e32 v6, vcc, 0x8203000, v6
	v_pk_mul_f32 v[4:5], v[4:5], v[0:1] op_sel_hi:[1,0]
	s_nop 0
	v_addc_co_u32_e32 v7, vcc, 0, v7, vcc
	s_andn2_b64 vcc, exec, s[8:9]
	v_pk_fma_f32 v[4:5], v[8:9], v[4:5], v[12:13]
	global_store_dwordx2 v[6:7], v[4:5], off
	s_cbranch_vccnz .LBB0_656
	v_readlane_b32 s0, v254, 32
	v_readlane_b32 s1, v254, 33
	v_ashrrev_i32_e32 v12, 6, v158
	v_ashrrev_i32_e32 v13, 31, v12
	v_lshl_add_u64 v[16:17], v[66:67], 1, s[0:1]
	v_readlane_b32 s0, v253, 30
	v_lshlrev_b64 v[14:15], 16, v[12:13]
	s_nop 0
	v_mov_b32_e32 v0, s0
	ds_read_b128 v[6:9], v0
	s_waitcnt lgkmcnt(0)
	v_lshl_add_u64 v[18:19], v[6:7], 0, v[14:15]
	v_lshlrev_b32_e32 v6, 7, v12
	v_ashrrev_i32_e32 v7, 31, v6
	v_lshl_add_u64 v[6:7], v[6:7], 2, v[8:9]
	v_lshl_add_u64 v[12:13], s[92:93], 1, v[16:17]
	global_load_dwordx4 v[6:9], v[6:7], off
	s_nop 0
	global_load_dword v0, v[18:19], off
	global_load_dword v15, v[12:13], off
	s_waitcnt vmcnt(1)
	v_pk_fma_f32 v[20:21], v[68:69], v[0:1], v[6:7] op_sel_hi:[1,0,0]
	s_waitcnt vmcnt(0)
	v_lshlrev_b32_e32 v14, 16, v15
	v_and_b32_e32 v15, 0xffff0000, v15
	v_pk_mul_f32 v[14:15], v[20:21], v[14:15]
	s_nop 0
	v_cvt_pk_bf16_f32 v0, v14, v15
	global_store_dword v[12:13], v0, off
	global_load_dwordx2 v[12:13], v[18:19], off offset:512
	v_lshl_add_u64 v[14:15], s[6:7], 1, v[16:17]
	global_load_dword v0, v[14:15], off
	s_waitcnt vmcnt(1)
	v_pk_fma_f32 v[6:7], v[68:69], v[12:13], v[6:7] op_sel:[0,0,1] op_sel_hi:[1,0,1]
	s_nop 0
	v_pk_fma_f32 v[6:7], v[2:3], v[12:13], v[6:7] op_sel:[0,1,0]
	s_waitcnt vmcnt(0)
	v_lshlrev_b32_e32 v20, 16, v0
	v_and_b32_e32 v21, 0xffff0000, v0
	v_pk_mul_f32 v[6:7], v[6:7], v[20:21]
	s_nop 0
	v_cvt_pk_bf16_f32 v0, v6, v7
	global_store_dword v[14:15], v0, off
	global_load_dwordx3 v[12:14], v[18:19], off offset:1024
	v_lshl_add_u64 v[6:7], s[4:5], 1, v[16:17]
	global_load_dword v0, v[6:7], off
	s_waitcnt vmcnt(1)
	v_pk_fma_f32 v[22:23], v[68:69], v[12:13], v[8:9] op_sel_hi:[1,0,0]
	s_nop 0
	v_pk_fma_f32 v[12:13], v[2:3], v[12:13], v[22:23] op_sel:[0,1,0]
	s_waitcnt vmcnt(0)
	v_lshlrev_b32_e32 v20, 16, v0
	v_and_b32_e32 v21, 0xffff0000, v0
	v_mov_b32_e32 v0, v14
	v_pk_fma_f32 v[12:13], v[10:11], v[0:1], v[12:13] op_sel_hi:[1,0,1]
	s_nop 0
	v_pk_mul_f32 v[12:13], v[12:13], v[20:21]
	s_nop 0
	v_cvt_pk_bf16_f32 v0, v12, v13
	global_store_dword v[6:7], v0, off
	v_lshl_add_u64 v[6:7], s[2:3], 1, v[16:17]
	global_load_dword v0, v[6:7], off
	global_load_dwordx4 v[12:15], v[18:19], off offset:1536
	s_waitcnt vmcnt(1)
	v_lshlrev_b32_e32 v16, 16, v0
	v_and_b32_e32 v17, 0xffff0000, v0
	v_mov_b32_e32 v0, v9
	s_waitcnt vmcnt(0)
	v_pk_fma_f32 v[8:9], v[68:69], v[12:13], v[0:1] op_sel_hi:[1,0,0]
	v_mov_b32_e32 v0, v15
	v_pk_fma_f32 v[2:3], v[2:3], v[12:13], v[8:9] op_sel:[0,1,0]
	s_nop 0
	v_pk_fma_f32 v[2:3], v[10:11], v[14:15], v[2:3] op_sel_hi:[1,0,1]
	s_nop 0
	v_pk_fma_f32 v[2:3], v[4:5], v[0:1], v[2:3] op_sel_hi:[1,0,1]
	s_nop 0
	v_pk_mul_f32 v[2:3], v[2:3], v[16:17]
	s_nop 0
	v_cvt_pk_bf16_f32 v0, v2, v3
	global_store_dword v[6:7], v0, off
